# mLSTM chunk loop: branch-free decay weights (4 ds_read + pipelined exp + cndmask per key block) on top of NA branch-free bias
# baseline (speedup 1.0000x reference)
; DI f32x4 mfma16(bf16x8 a, bf16x8 b, f32x4 c) { return __builtin_amdgcn_mfma_f32_16x16x32_bf16(a, b, c, 0, 0, 0); }
; __device__ void mlstm_chain(const Params& p, int layer, int idx, char* smem) {
;     ...
;     if (i + 1 < 36) {
;       const int nb = chunk_base(i + 1);
;       const size_t ro = (size_t)(nb + (dir ? 63 - lrow : lrow)) * ZW;
;       nq = *(const u32x4*)(Z + ro + MQ + h * 64 + c8 * 8);
;       nk = *(const u32x4*)(Z + ro + MK + h * 64 + c8 * 8);
;       nv = *(const u32x4*)(Z + ro + MV + h * 64 + c8 * 8);
;     }
;     {
;       const int tb = (w < 4) ? w : 7 - w, vh = w >> 2;
;       const int t = tb * 16 + c;
;       const float Mt = fmaxf(mprev, cms[t]);
;       const float win = __expf(mprev - Mt);
;       bf16x8 qf[2];
; #pragma unroll
;       for (int kk = 0; kk < 2; ++kk) qf[kk] = ld_frag16(Qs + t * 72 + 32 * kk + 8 * g);
;       float psum = 0.f;
;       unsigned pp[4][2];
; #pragma unroll
;       for (int st = 0; st < 4; ++st) {
;         f32x4 sacc = (f32x4){0.f, 0.f, 0.f, 0.f};
;         if (st <= tb) {
; #pragma unroll
;           for (int kk = 0; kk < 2; ++kk) sacc = mfma16(ld_frag16(Ksm + (st * 16 + c) * 72 + 32 * kk + 8 * g), qf[kk], sacc);
; #pragma unroll
;           for (int rg = 0; rg < 4; ++rg) {
;             const int s = st * 16 + 4 * g + rg;
;             const float dv = (s <= t) ? __expf(us[s] - Mt) : 0.f;
;             sacc[rg] *= dv;
;             psum += sacc[rg];
;           }
;         }
;         pp[st][0] = pk_bf16(sacc[0], sacc[1]);
;         pp[st][1] = pk_bf16(sacc[2], sacc[3]);
;       }
.LBB0_553:
	s_lshl_b32 s17, s74, 6
	s_add_i32 s17, s17, s16
	v_add_u32_e32 v10, s17, v60
	v_mad_i64_i32 v[14:15], s[16:17], v10, s79, v[38:39]
	global_load_dwordx4 v[18:21], v[14:15], off offset:2560
	global_load_dwordx4 v[10:13], v[14:15], off offset:3072
	s_nop 0
	global_load_dwordx4 v[14:17], v[14:15], off offset:3584
	v_add_u32_e32 v53, s29, v65
	ds_read_b32 v22, v53 offset:18432
	v_add3_u32 v70, s73, v56, v49
	v_add_u32_e32 v30, s72, v49
	v_cndmask_b32_e64 v31, 0, 1, s[8:9]
	v_cmp_ne_u32_e64 s[72:73], 1, v31
	s_waitcnt lgkmcnt(0)
	v_max_f32_e32 v22, v22, v22
	v_max_f32_e32 v41, v0, v22
	ds_read_b128 v[26:29], v70
	ds_read_b128 v[22:25], v70 offset:64
	v_mov_b32_e32 v0, 0
	s_andn2_b64 vcc, exec, s[8:9]
	v_add_u32_e32 v75, v30, v59
	v_mov_b32_e32 v73, 0
	v_mov_b32_e32 v72, 0
	v_mov_b32_e32 v71, 0
	v_mov_b32_e32 v74, 0
	s_cbranch_vccnz .LBB0_563
	ds_read_b128 v[30:33], v75
	ds_read_b128 v[76:79], v75 offset:64
	v_mov_b32_e32 v0, 0
	v_mov_b32_e32 v72, 0
	s_waitcnt lgkmcnt(1)
	v_mfma_f32_16x16x32_bf16 v[30:33], v[30:33], v[26:29], 0
	s_waitcnt lgkmcnt(0)
	v_mfma_f32_16x16x32_bf16 v[30:33], v[76:79], v[22:25], v[30:33]
	v_add_u32_e32 v71, s29, v66
	ds_read_b32 v72, v71 offset:54272
	ds_read_b32 v73, v71 offset:54276
	ds_read_b32 v0, v71 offset:54280
	ds_read_b32 v76, v71 offset:54284
	s_waitcnt lgkmcnt(0)
	v_sub_f32_e32 v72, v72, v41
	v_sub_f32_e32 v73, v73, v41
	v_sub_f32_e32 v0, v0, v41
	v_sub_f32_e32 v76, v76, v41
	v_mul_f32_e32 v72, 0x3fb8aa3b, v72
	v_mul_f32_e32 v73, 0x3fb8aa3b, v73
	v_mul_f32_e32 v0, 0x3fb8aa3b, v0
	v_mul_f32_e32 v76, 0x3fb8aa3b, v76
	v_exp_f32_e32 v72, v72
	v_exp_f32_e32 v73, v73
	v_exp_f32_e32 v0, v0
	v_exp_f32_e32 v76, v76
	v_cndmask_b32_e64 v72, 0, v72, s[70:71]
	v_cndmask_b32_e64 v73, 0, v73, s[68:69]
	v_cndmask_b32_e64 v0, 0, v0, s[66:67]
	v_cndmask_b32_e64 v76, 0, v76, s[64:65]
	v_fma_f32 v74, v30, v72, 0
	v_fmac_f32_e32 v74, v31, v73
	v_fmac_f32_e32 v74, v32, v0
	v_mul_f32_e32 v71, v30, v72
	v_mul_f32_e32 v72, v31, v73
	v_mul_f32_e32 v73, v32, v0
	v_mul_f32_e32 v0, v33, v76
	v_fmac_f32_e32 v74, v33, v76
.LBB0_563:
	v_cndmask_b32_e64 v30, 0, 1, s[10:11]
	v_cmp_ne_u32_e64 s[74:75], 1, v30
	s_andn2_b64 vcc, exec, s[10:11]
	v_mov_b32_e32 v77, 0
	s_cbranch_vccnz .LBB0_568
	ds_read_b128 v[30:33], v75 offset:2304
	ds_read_b128 v[76:79], v75 offset:2368
	s_waitcnt lgkmcnt(1)
	v_mfma_f32_16x16x32_bf16 v[30:33], v[30:33], v[26:29], 0
	s_waitcnt lgkmcnt(0)
	v_mfma_f32_16x16x32_bf16 v[30:33], v[76:79], v[22:25], v[30:33]
	v_add_u32_e32 v76, s29, v66
	ds_read_b32 v78, v76 offset:54336
	ds_read_b32 v79, v76 offset:54340
	ds_read_b32 v77, v76 offset:54344
	ds_read_b32 v80, v76 offset:54348
	s_waitcnt lgkmcnt(0)
	v_sub_f32_e32 v78, v78, v41
	v_sub_f32_e32 v79, v79, v41
	v_sub_f32_e32 v77, v77, v41
	v_sub_f32_e32 v80, v80, v41
	v_mul_f32_e32 v78, 0x3fb8aa3b, v78
	v_mul_f32_e32 v79, 0x3fb8aa3b, v79
	v_mul_f32_e32 v77, 0x3fb8aa3b, v77
	v_mul_f32_e32 v80, 0x3fb8aa3b, v80
	v_exp_f32_e32 v78, v78
	v_exp_f32_e32 v79, v79
	v_exp_f32_e32 v77, v77
	v_exp_f32_e32 v80, v80
	v_cndmask_b32_e64 v78, 0, v78, s[62:63]
	v_cndmask_b32_e64 v79, 0, v79, s[60:61]
	v_cndmask_b32_e64 v77, 0, v77, s[58:59]
	v_cndmask_b32_e64 v80, 0, v80, s[56:57]
	v_fmac_f32_e32 v74, v30, v78
	v_fmac_f32_e32 v74, v31, v79
	v_fmac_f32_e32 v74, v32, v77
	v_mul_f32_e32 v76, v30, v78
	v_mul_f32_e32 v78, v31, v79
	v_mul_f32_e32 v79, v32, v77
	v_mul_f32_e32 v77, v33, v80
	v_fmac_f32_e32 v74, v33, v80
.LBB0_574:
	v_cndmask_b32_e64 v30, 0, 1, s[12:13]
	v_cmp_ne_u32_e64 s[76:77], 1, v30
	s_andn2_b64 vcc, exec, s[12:13]
	v_mov_b32_e32 v81, 0
	s_cbranch_vccnz .LBB0_579
	ds_read_b128 v[30:33], v75 offset:4608
	ds_read_b128 v[80:83], v75 offset:4672
	s_waitcnt lgkmcnt(1)
	v_mfma_f32_16x16x32_bf16 v[30:33], v[30:33], v[26:29], 0
	s_waitcnt lgkmcnt(0)
	v_mfma_f32_16x16x32_bf16 v[30:33], v[80:83], v[22:25], v[30:33]
	v_add_u32_e32 v80, s29, v66
	ds_read_b32 v82, v80 offset:54400
	ds_read_b32 v83, v80 offset:54404
	ds_read_b32 v81, v80 offset:54408
	ds_read_b32 v84, v80 offset:54412
	s_waitcnt lgkmcnt(0)
	v_sub_f32_e32 v82, v82, v41
	v_sub_f32_e32 v83, v83, v41
	v_sub_f32_e32 v81, v81, v41
	v_sub_f32_e32 v84, v84, v41
	v_mul_f32_e32 v82, 0x3fb8aa3b, v82
	v_mul_f32_e32 v83, 0x3fb8aa3b, v83
	v_mul_f32_e32 v81, 0x3fb8aa3b, v81
	v_mul_f32_e32 v84, 0x3fb8aa3b, v84
	v_exp_f32_e32 v82, v82
	v_exp_f32_e32 v83, v83
	v_exp_f32_e32 v81, v81
	v_exp_f32_e32 v84, v84
	v_cndmask_b32_e64 v82, 0, v82, s[54:55]
	v_cndmask_b32_e64 v83, 0, v83, s[52:53]
	v_cndmask_b32_e64 v81, 0, v81, s[50:51]
	v_cndmask_b32_e64 v84, 0, v84, s[48:49]
	v_fmac_f32_e32 v74, v30, v82
	v_fmac_f32_e32 v74, v31, v83
	v_fmac_f32_e32 v74, v32, v81
	v_mul_f32_e32 v80, v30, v82
	v_mul_f32_e32 v82, v31, v83
	v_mul_f32_e32 v83, v32, v81
	v_mul_f32_e32 v81, v33, v84
	v_fmac_f32_e32 v74, v33, v84
	s_mov_b64 s[16:17], -1
	s_and_b64 vcc, exec, s[6:7]
	s_cbranch_vccz .LBB0_594
.LBB0_585:
	ds_read_b128 v[30:33], v75 offset:6912
	ds_read_b128 v[84:87], v75 offset:6976
	v_mov_b32_e32 v75, 0
	s_waitcnt lgkmcnt(1)
	v_mfma_f32_16x16x32_bf16 v[30:33], v[30:33], v[26:29], 0
	s_waitcnt lgkmcnt(0)
	v_mfma_f32_16x16x32_bf16 v[30:33], v[84:87], v[22:25], v[30:33]
	v_add_u32_e32 v84, s29, v66
	ds_read_b32 v85, v84 offset:54464
	ds_read_b32 v86, v84 offset:54468
	ds_read_b32 v75, v84 offset:54472
	ds_read_b32 v87, v84 offset:54476
	s_waitcnt lgkmcnt(0)
	v_sub_f32_e32 v85, v85, v41
	v_sub_f32_e32 v86, v86, v41
	v_sub_f32_e32 v75, v75, v41
	v_sub_f32_e32 v87, v87, v41
	v_mul_f32_e32 v85, 0x3fb8aa3b, v85
	v_mul_f32_e32 v86, 0x3fb8aa3b, v86
	v_mul_f32_e32 v75, 0x3fb8aa3b, v75
	v_mul_f32_e32 v87, 0x3fb8aa3b, v87
	v_exp_f32_e32 v85, v85
	v_exp_f32_e32 v86, v86
	v_exp_f32_e32 v75, v75
	v_exp_f32_e32 v87, v87
	v_cndmask_b32_e64 v85, 0, v85, s[46:47]
	v_cndmask_b32_e64 v86, 0, v86, s[44:45]
	v_cndmask_b32_e64 v75, 0, v75, s[42:43]
	v_cndmask_b32_e64 v87, 0, v87, s[40:41]
	v_mul_f32_e32 v84, v30, v85
	v_fma_f32 v30, v30, v85, v74
	v_fmac_f32_e32 v30, v31, v86
	v_fmac_f32_e32 v30, v32, v75
	v_mul_f32_e32 v85, v31, v86
	v_mul_f32_e32 v31, v32, v75
	v_mul_f32_e32 v32, v33, v87
	v_fmac_f32_e32 v30, v33, v87
	s_mov_b64 s[16:17], 0

; DI u16 f2bf(float a) { return (u16)(pk_bf16(a, 0.f) & 0xffffu); }
; DI float bf_lo(unsigned u) { return __uint_as_float(u << 16); }
; DI float bf_hi(unsigned u) { return __uint_as_float(u & 0xffff0000u); }
; __device__ void mlstm_chain(const Params& p, int layer, int idx, char* smem) {
;     ...
;     const float* bs = bsA + i * 64;
;     const float* us = usA + i * 64;
;     const float* cms = cmA + i * 64;
;     const float Mend = fmaxf(mprev, cms[63]);
;     const float wold = __expf(mprev - Mend);
;     const float mnew = bs[63] + Mend;
;     *(u32x4*)(Qs + lrow * 72 + c8 * 8) = nq;
;     *(u32x4*)(Ksm + lrow * 72 + c8 * 8) = nk;
;     {
;       const float ws = __expf(us[lrow] - Mend);
; #pragma unroll
;       for (int j = 0; j < 4; ++j) {
;         VT[(c8 * 8 + 2 * j) * 66 + lrow] = (u16)(nv[j] & 0xffffu);
;         VT[(c8 * 8 + 2 * j + 1) * 66 + lrow] = (u16)(nv[j] >> 16);
;         KTw[(c8 * 8 + 2 * j) * 66 + lrow] = f2bf(bf_lo(nk[j]) * ws);
;         KTw[(c8 * 8 + 2 * j + 1) * 66 + lrow] = f2bf(bf_hi(nk[j]) * ws);
;       }
;     }
;     lds_barrier();
;     if (i + 1 < 36) {
;       const int nb = chunk_base(i + 1);
;       const size_t ro = (size_t)(nb + (dir ? 63 - lrow : lrow)) * ZW;
;       nq = *(const u32x4*)(Z + ro + MQ + h * 64 + c8 * 8);
;       nk = *(const u32x4*)(Z + ro + MK + h * 64 + c8 * 8);
;       nv = *(const u32x4*)(Z + ro + MV + h * 64 + c8 * 8);
;     }
;     {
;       const int tb = (w < 4) ? w : 7 - w, vh = w >> 2;
;       const int t = tb * 16 + c;
;       const float Mt = fmaxf(mprev, cms[t]);
;       const float win = __expf(mprev - Mt);
;       bf16x8 qf[2];
; #pragma unroll
;       for (int kk = 0; kk < 2; ++kk) qf[kk] = ld_frag16(Qs + t * 72 + 32 * kk + 8 * g);
;       float psum = 0.f;
;       unsigned pp[4][2];
; #pragma unroll
;       for (int st = 0; st < 4; ++st) {
;         f32x4 sacc = (f32x4){0.f, 0.f, 0.f, 0.f};
;         if (st <= tb) {
; #pragma unroll
;           for (int kk = 0; kk < 2; ++kk) sacc = mfma16(ld_frag16(Ksm + (st * 16 + c) * 72 + 32 * kk + 8 * g), qf[kk], sacc);
; #pragma unroll
;           for (int rg = 0; rg < 4; ++rg) {
;             const int s = st * 16 + 4 * g + rg;
;             const float dv = (s <= t) ? __expf(us[s] - Mt) : 0.f;
;             sacc[rg] *= dv;
;             psum += sacc[rg];
;           }
;         }
.LBB0_598:
	s_or_b64 exec, exec, s[16:17]
	s_add_i32 s27, s27, -1
	s_add_i32 s28, s28, 1
	s_addk_i32 s29, 0x100
	s_cmp_lg_u32 s27, -1
	v_add_f32_e32 v54, v40, v69
	s_cbranch_scc0 .LBB0_600
	s_movk_i32 s79, 0x1c00
	s_branch .LBB0_545
.LBB0_568:
	v_mov_b32_e32 v79, 0
	v_mov_b32_e32 v78, 0
	v_mov_b32_e32 v76, 0
	s_branch .LBB0_574
.LBB0_579:
	v_mov_b32_e32 v83, 0
	v_mov_b32_e32 v82, 0
	v_mov_b32_e32 v80, 0
	s_mov_b64 s[16:17], -1
	s_and_b64 vcc, exec, s[6:7]
	s_cbranch_vccz .LBB0_594
	s_branch .LBB0_585
.LBB0_600:
	v_readlane_b32 s8, v254, 26
	v_add3_u32 v24, s30, v67, v42
	v_lshl_add_u32 v32, v55, 2, 0
	v_mov_b32_e32 v0, s8
	ds_read_b32 v0, v0
	s_waitcnt vmcnt(4)
	ds_write_b128 v24, v[18:21]
	v_add3_u32 v18, s31, v67, v42
	s_waitcnt vmcnt(3)
	ds_write_b128 v18, v[10:13]
	ds_read_b32 v18, v32 offset:63232
	s_waitcnt lgkmcnt(3)
	v_max_f32_e32 v0, v0, v0
	v_max_f32_e32 v20, v54, v54
	v_max_f32_e32 v0, v20, v0
	v_add_u32_e32 v21, s24, v63
	s_waitcnt lgkmcnt(0)
	v_sub_f32_e32 v18, v18, v0
	v_mul_f32_e32 v18, 0x3fb8aa3b, v18
	v_exp_f32_e32 v18, v18
	s_waitcnt vmcnt(2)
	ds_write_b16 v21, v14
	v_add_u32_e32 v21, s24, v62
	ds_write_b16_d16_hi v21, v14
	v_lshlrev_b32_e32 v14, 16, v10
	v_mul_f32_e32 v14, v18, v14
	v_and_b32_e32 v10, 0xffff0000, v10
	v_cvt_pk_bf16_f32 v14, v14, s0
	v_add_u32_e32 v21, s23, v63
	v_mul_f32_e32 v10, v18, v10
	v_add_u32_e32 v22, 0x84, v61
	ds_write_b16 v21, v14
	v_cvt_pk_bf16_f32 v10, v10, s0
	v_add_u32_e32 v14, s23, v62
	ds_write_b16 v14, v10
	v_add_lshl_u32 v10, v22, v55, 1
	v_add_u32_e32 v14, s24, v10
	ds_write_b16 v14, v15
	v_add_lshl_u32 v14, v22, v58, 1
	v_add_u32_e32 v21, s24, v14
	ds_write_b16_d16_hi v21, v15
	v_lshlrev_b32_e32 v15, 16, v11
	v_mul_f32_e32 v15, v18, v15
	v_cvt_pk_bf16_f32 v15, v15, s0
	v_add_u32_e32 v10, s23, v10
	ds_write_b16 v10, v15
	v_and_b32_e32 v10, 0xffff0000, v11
	v_mul_f32_e32 v10, v18, v10
	v_add_u32_e32 v23, 0x108, v61
	v_cvt_pk_bf16_f32 v10, v10, s0
	v_add_u32_e32 v11, s23, v14
	ds_write_b16 v11, v10
	v_add_lshl_u32 v10, v23, v55, 1
	v_add_u32_e32 v11, s24, v10
	ds_write_b16 v11, v16
	v_add_lshl_u32 v11, v23, v58, 1
	v_add_u32_e32 v14, s24, v11
	ds_write_b16_d16_hi v14, v16
	v_lshlrev_b32_e32 v14, 16, v12
	v_mul_f32_e32 v14, v18, v14
	v_cvt_pk_bf16_f32 v14, v14, s0
	v_add_u32_e32 v10, s23, v10
	ds_write_b16 v10, v14
	v_and_b32_e32 v10, 0xffff0000, v12
	v_mul_f32_e32 v10, v18, v10
	v_add_u32_e32 v19, 0x18c, v61
	v_cvt_pk_bf16_f32 v10, v10, s0
	v_add_u32_e32 v11, s23, v11
	ds_write_b16 v11, v10
	v_add_lshl_u32 v10, v19, v55, 1
	v_add_u32_e32 v11, s24, v10
	ds_write_b16 v11, v17
	v_add_lshl_u32 v11, v19, v58, 1
	v_add_u32_e32 v12, s24, v11
	ds_write_b16_d16_hi v12, v17
	v_lshlrev_b32_e32 v12, 16, v13
	v_mul_f32_e32 v12, v18, v12
	v_cvt_pk_bf16_f32 v12, v12, s0
	v_add_u32_e32 v10, s23, v10
	ds_write_b16 v10, v12
	v_and_b32_e32 v10, 0xffff0000, v13
	v_mul_f32_e32 v10, v18, v10
	v_cvt_pk_bf16_f32 v10, v10, s0
	v_add_u32_e32 v11, s23, v11
	ds_write_b16 v11, v10
	v_lshl_add_u32 v28, v57, 2, 0
	s_waitcnt lgkmcnt(0)
	s_barrier
	v_add_u32_e32 v10, 0x11b00, v28
	ds_read_b32 v10, v10
	v_add3_u32 v26, s30, v56, v49
	v_add_u32_e32 v18, s31, v49
	v_mov_b32_e32 v23, 0
	s_and_b64 vcc, exec, s[72:73]
	s_waitcnt lgkmcnt(0)
	v_max_f32_e32 v10, v10, v10
	v_max_f32_e32 v30, v20, v10
	ds_read_b128 v[14:17], v26
	ds_read_b128 v[10:13], v26 offset:64
	v_add_u32_e32 v25, v18, v59
	v_mov_b32_e32 v38, 0
	v_mov_b32_e32 v31, 0
	v_mov_b32_e32 v22, 0
	v_mov_b32_e32 v24, 0
	s_cbranch_vccnz .LBB0_610
	ds_read_b128 v[18:21], v25
	ds_read_b128 v[56:59], v25 offset:64
	v_mov_b32_e32 v23, 0
	v_mov_b32_e32 v24, 0
	s_waitcnt lgkmcnt(1)
	v_mfma_f32_16x16x32_bf16 v[18:21], v[18:21], v[14:17], 0
	s_waitcnt lgkmcnt(0)
	v_mfma_f32_16x16x32_bf16 v[18:21], v[56:59], v[10:13], v[18:21]
	s_and_saveexec_b64 s[8:9], s[70:71]
	s_cbranch_execz .LBB0_605
	v_lshl_add_u32 v22, v52, 2, 0
	ds_read_b32 v22, v22 offset:63232
	s_waitcnt lgkmcnt(0)
	v_sub_f32_e32 v22, v22, v30
	v_mul_f32_e32 v22, 0x3fb8aa3b, v22
	v_exp_f32_e32 v24, v22
	s_or_b64 exec, exec, s[8:9]
	v_mov_b32_e32 v38, 0
	s_and_saveexec_b64 s[8:9], s[68:69]
	s_cbranch_execnz .LBB0_606
